# layer-0 sample-row finalize (phase 9): all 37 loads of a row in flight, scalar addressing, replaces the compiler's wait-per-load loop
# baseline (speedup 1.0000x reference)
; __device__ __forceinline__ float bf_lo(unsigned w) { return __uint_as_float(w << 16); }
; __device__ __forceinline__ float bf_hi(unsigned w) { return __uint_as_float(w & 0xffff0000u); }
; __device__ __forceinline__ unsigned pk2(float lo, float hi) { return pg8::cvt_pk_bf16(lo, hi); }
; __device__ __forceinline__ void phase_sample_finalize(const Args& a, unsigned char* ws, int G, const int bid, const int tid) {
;     ...
;     for (int r = bid * 8 + wave; r < MS; r += G * 8) {
;         const int m = MP + r; float ss = 0.f; u32x2 o[4];
;         const float r2 = __builtin_amdgcn_rcpf(rs1[m] * (1.0f / DM) + EPS);
; #pragma unroll
;         for (int j = 0; j < 4; ++j) { const u32x2 w = ((const u32x2*)(XB + (size_t)m * DM))[lane + 64 * j]; f32x4 v = {pg8::bf_lo(w.x), pg8::bf_hi(w.x), pg8::bf_lo(w.y), pg8::bf_hi(w.y)};
;             f32x4 p = {0.f, 0.f, 0.f, 0.f};
; #pragma unroll
;             for (int z = 0; z < 8; ++z) { const u32x2 sw = ((const u32x2*)(SL + ((size_t)z * MS + r) * DM))[lane + 64 * j]; p += (f32x4){pg8::bf_lo(sw.x), pg8::bf_hi(sw.x), pg8::bf_lo(sw.y), pg8::bf_hi(sw.y)}; }
;             v += p * r2;
;             ss += (v.x * v.x + v.y * v.y) + (v.z * v.z + v.w * v.w); o[j] = (u32x2){pk2(v.x, v.y), pk2(v.z, v.w)}; }
.Lmid_next:
	v_readlane_b32 s12, v254, 33
	v_readlane_b32 s13, v254, 34
	v_add_u32_e32 v11, s94, v11
	s_nop 0
	v_lshl_add_u64 v[0:1], v[0:1], 0, s[12:13]
	v_lshl_add_u64 v[2:3], v[2:3], 0, s[12:13]
	s_movk_i32 s12, 0x7ff
	v_cmp_lt_i32_e32 vcc, s12, v11
	v_readlane_b32 s12, v254, 38
	v_readlane_b32 s13, v254, 39
	s_or_b64 s[10:11], vcc, s[10:11]
	s_nop 0
	v_lshl_add_u64 v[4:5], v[4:5], 0, s[12:13]
	s_andn2_b64 exec, exec, s[10:11]
	s_cbranch_execz .LBB0_78
.LBB0_24:
.Lmid_row:
	v_readfirstlane_b32 s18, v11
	v_and_b32_e32 v34, 63, v162
	v_lshlrev_b32_e32 v16, 3, v34
	v_lshlrev_b32_e32 v17, 2, v34
	s_nop 0
	s_add_u32 s19, s18, 0x10000
	s_lshl_b32 s20, s19, 11
	s_add_u32 s12, s26, s20
	s_addc_u32 s13, s27, 0
	s_add_u32 s12, s12, 0x4800000
	s_addc_u32 s13, s13, 0
	s_lshl_b32 s20, s19, 2
	s_add_u32 s14, s26, s20
	s_addc_u32 s15, s27, 0
	s_load_dword s20, s[14:15], 0x42000
	s_lshl_b32 s19, s18, 11
	s_add_u32 s16, s26, s19
	s_addc_u32 s17, s27, 0
	s_add_u32 s16, s16, 0x2dc00000
	s_addc_u32 s17, s17, 0
	global_load_dwordx2 v[26:27], v16, s[12:13] offset:0
	global_load_dwordx2 v[28:29], v16, s[12:13] offset:512
	global_load_dwordx2 v[30:31], v16, s[12:13] offset:1024
	global_load_dwordx2 v[32:33], v16, s[12:13] offset:1536
	global_load_dwordx2 v[64:65], v16, s[16:17] offset:0
	global_load_dwordx2 v[66:67], v16, s[16:17] offset:512
	global_load_dwordx2 v[68:69], v16, s[16:17] offset:1024
	global_load_dwordx2 v[70:71], v16, s[16:17] offset:1536
	s_add_u32 s16, s16, 0x400000
	s_addc_u32 s17, s17, 0
	global_load_dwordx2 v[72:73], v16, s[16:17] offset:0
	global_load_dwordx2 v[74:75], v16, s[16:17] offset:512
	global_load_dwordx2 v[76:77], v16, s[16:17] offset:1024
	global_load_dwordx2 v[78:79], v16, s[16:17] offset:1536
	s_add_u32 s16, s16, 0x400000
	s_addc_u32 s17, s17, 0
	global_load_dwordx2 v[80:81], v16, s[16:17] offset:0
	global_load_dwordx2 v[82:83], v16, s[16:17] offset:512
	global_load_dwordx2 v[84:85], v16, s[16:17] offset:1024
	global_load_dwordx2 v[86:87], v16, s[16:17] offset:1536
	s_add_u32 s16, s16, 0x400000
	s_addc_u32 s17, s17, 0
	global_load_dwordx2 v[88:89], v16, s[16:17] offset:0
	global_load_dwordx2 v[90:91], v16, s[16:17] offset:512
	global_load_dwordx2 v[92:93], v16, s[16:17] offset:1024
	global_load_dwordx2 v[94:95], v16, s[16:17] offset:1536
	s_add_u32 s16, s16, 0x400000
	s_addc_u32 s17, s17, 0
	global_load_dwordx2 v[96:97], v16, s[16:17] offset:0
	global_load_dwordx2 v[98:99], v16, s[16:17] offset:512
	global_load_dwordx2 v[100:101], v16, s[16:17] offset:1024
	global_load_dwordx2 v[102:103], v16, s[16:17] offset:1536
	s_add_u32 s16, s16, 0x400000
	s_addc_u32 s17, s17, 0
	global_load_dwordx2 v[104:105], v16, s[16:17] offset:0
	global_load_dwordx2 v[106:107], v16, s[16:17] offset:512
	global_load_dwordx2 v[108:109], v16, s[16:17] offset:1024
	global_load_dwordx2 v[110:111], v16, s[16:17] offset:1536
	s_add_u32 s16, s16, 0x400000
	s_addc_u32 s17, s17, 0
	global_load_dwordx2 v[112:113], v16, s[16:17] offset:0
	global_load_dwordx2 v[114:115], v16, s[16:17] offset:512
	global_load_dwordx2 v[116:117], v16, s[16:17] offset:1024
	global_load_dwordx2 v[118:119], v16, s[16:17] offset:1536
	s_add_u32 s16, s16, 0x400000
	s_addc_u32 s17, s17, 0
	global_load_dwordx2 v[120:121], v16, s[16:17] offset:0
	global_load_dwordx2 v[122:123], v16, s[16:17] offset:512
	global_load_dwordx2 v[124:125], v16, s[16:17] offset:1024
	global_load_dwordx2 v[126:127], v16, s[16:17] offset:1536
	s_waitcnt lgkmcnt(0)
	v_mov_b32_e32 v22, s20
	v_fmamk_f32 v22, v22, 0x3a800000, v197
	v_rcp_f32_e32 v22, v22
	v_mov_b32_e32 v23, 0
	s_waitcnt vmcnt(0)
	v_mov_b32_e32 v60, 0
	v_mov_b32_e32 v61, 0
	v_mov_b32_e32 v62, 0
	v_mov_b32_e32 v63, 0
	v_lshlrev_b32_e32 v34, 16, v64
	v_and_b32_e32 v52, 0xffff0000, v64
	v_lshlrev_b32_e32 v53, 16, v65
	v_and_b32_e32 v59, 0xffff0000, v65
	v_add_f32_e32 v60, v60, v34
	v_add_f32_e32 v61, v61, v52
	v_add_f32_e32 v62, v62, v53
	v_add_f32_e32 v63, v63, v59
	v_lshlrev_b32_e32 v34, 16, v72
	v_and_b32_e32 v52, 0xffff0000, v72
	v_lshlrev_b32_e32 v53, 16, v73
	v_and_b32_e32 v59, 0xffff0000, v73
	v_add_f32_e32 v60, v60, v34
	v_add_f32_e32 v61, v61, v52
	v_add_f32_e32 v62, v62, v53
	v_add_f32_e32 v63, v63, v59
	v_lshlrev_b32_e32 v34, 16, v80
	v_and_b32_e32 v52, 0xffff0000, v80
	v_lshlrev_b32_e32 v53, 16, v81
	v_and_b32_e32 v59, 0xffff0000, v81
	v_add_f32_e32 v60, v60, v34
	v_add_f32_e32 v61, v61, v52
	v_add_f32_e32 v62, v62, v53
	v_add_f32_e32 v63, v63, v59
	v_lshlrev_b32_e32 v34, 16, v88
	v_and_b32_e32 v52, 0xffff0000, v88
	v_lshlrev_b32_e32 v53, 16, v89
	v_and_b32_e32 v59, 0xffff0000, v89
	v_add_f32_e32 v60, v60, v34
	v_add_f32_e32 v61, v61, v52
	v_add_f32_e32 v62, v62, v53
	v_add_f32_e32 v63, v63, v59
	v_lshlrev_b32_e32 v34, 16, v96
	v_and_b32_e32 v52, 0xffff0000, v96
	v_lshlrev_b32_e32 v53, 16, v97
	v_and_b32_e32 v59, 0xffff0000, v97
	v_add_f32_e32 v60, v60, v34
	v_add_f32_e32 v61, v61, v52
	v_add_f32_e32 v62, v62, v53
	v_add_f32_e32 v63, v63, v59
	v_lshlrev_b32_e32 v34, 16, v104
	v_and_b32_e32 v52, 0xffff0000, v104
	v_lshlrev_b32_e32 v53, 16, v105
	v_and_b32_e32 v59, 0xffff0000, v105
	v_add_f32_e32 v60, v60, v34
	v_add_f32_e32 v61, v61, v52
	v_add_f32_e32 v62, v62, v53
	v_add_f32_e32 v63, v63, v59
	v_lshlrev_b32_e32 v34, 16, v112
	v_and_b32_e32 v52, 0xffff0000, v112
	v_lshlrev_b32_e32 v53, 16, v113
	v_and_b32_e32 v59, 0xffff0000, v113
	v_add_f32_e32 v60, v60, v34
	v_add_f32_e32 v61, v61, v52
	v_add_f32_e32 v62, v62, v53
	v_add_f32_e32 v63, v63, v59
	v_lshlrev_b32_e32 v34, 16, v120
	v_and_b32_e32 v52, 0xffff0000, v120
	v_lshlrev_b32_e32 v53, 16, v121
	v_and_b32_e32 v59, 0xffff0000, v121
	v_add_f32_e32 v60, v60, v34
	v_add_f32_e32 v61, v61, v52
; __device__ __forceinline__ float bf_lo(unsigned w) { return __uint_as_float(w << 16); }
; __device__ __forceinline__ float bf_hi(unsigned w) { return __uint_as_float(w & 0xffff0000u); }
; __device__ __forceinline__ unsigned pk2(float lo, float hi) { return pg8::cvt_pk_bf16(lo, hi); }
; __device__ __forceinline__ void phase_sample_finalize(const Args& a, unsigned char* ws, int G, const int bid, const int tid) {
;     ...
;         for (int j = 0; j < 4; ++j) { const u32x2 w = ((const u32x2*)(XB + (size_t)m * DM))[lane + 64 * j]; f32x4 v = {pg8::bf_lo(w.x), pg8::bf_hi(w.x), pg8::bf_lo(w.y), pg8::bf_hi(w.y)};
;             f32x4 p = {0.f, 0.f, 0.f, 0.f};
; #pragma unroll
;             for (int z = 0; z < 8; ++z) { const u32x2 sw = ((const u32x2*)(SL + ((size_t)z * MS + r) * DM))[lane + 64 * j]; p += (f32x4){pg8::bf_lo(sw.x), pg8::bf_hi(sw.x), pg8::bf_lo(sw.y), pg8::bf_hi(sw.y)}; }
;             v += p * r2;
;             ss += (v.x * v.x + v.y * v.y) + (v.z * v.z + v.w * v.w); o[j] = (u32x2){pk2(v.x, v.y), pk2(v.z, v.w)}; }
	v_add_f32_e32 v62, v62, v53
	v_add_f32_e32 v63, v63, v59
	v_lshlrev_b32_e32 v34, 16, v26
	v_and_b32_e32 v52, 0xffff0000, v26
	v_lshlrev_b32_e32 v53, 16, v27
	v_and_b32_e32 v59, 0xffff0000, v27
	v_fma_f32 v36, v60, v22, v34
	v_fma_f32 v37, v61, v22, v52
	v_fma_f32 v38, v62, v22, v53
	v_fma_f32 v39, v63, v22, v59
	v_mul_f32_e32 v34, v36, v36
	v_fma_f32 v34, v37, v37, v34
	v_mul_f32_e32 v52, v38, v38
	v_fma_f32 v52, v39, v39, v52
	v_add_f32_e32 v34, v34, v52
	v_add_f32_e32 v23, v23, v34
	v_mov_b32_e32 v60, 0
	v_mov_b32_e32 v61, 0
	v_mov_b32_e32 v62, 0
	v_mov_b32_e32 v63, 0
	v_lshlrev_b32_e32 v34, 16, v66
	v_and_b32_e32 v52, 0xffff0000, v66
	v_lshlrev_b32_e32 v53, 16, v67
	v_and_b32_e32 v59, 0xffff0000, v67
	v_add_f32_e32 v60, v60, v34
	v_add_f32_e32 v61, v61, v52
	v_add_f32_e32 v62, v62, v53
	v_add_f32_e32 v63, v63, v59
	v_lshlrev_b32_e32 v34, 16, v74
	v_and_b32_e32 v52, 0xffff0000, v74
	v_lshlrev_b32_e32 v53, 16, v75
	v_and_b32_e32 v59, 0xffff0000, v75
	v_add_f32_e32 v60, v60, v34
	v_add_f32_e32 v61, v61, v52
	v_add_f32_e32 v62, v62, v53
	v_add_f32_e32 v63, v63, v59
	v_lshlrev_b32_e32 v34, 16, v82
	v_and_b32_e32 v52, 0xffff0000, v82
	v_lshlrev_b32_e32 v53, 16, v83
	v_and_b32_e32 v59, 0xffff0000, v83
	v_add_f32_e32 v60, v60, v34
	v_add_f32_e32 v61, v61, v52
	v_add_f32_e32 v62, v62, v53
	v_add_f32_e32 v63, v63, v59
	v_lshlrev_b32_e32 v34, 16, v90
	v_and_b32_e32 v52, 0xffff0000, v90
	v_lshlrev_b32_e32 v53, 16, v91
	v_and_b32_e32 v59, 0xffff0000, v91
	v_add_f32_e32 v60, v60, v34
	v_add_f32_e32 v61, v61, v52
	v_add_f32_e32 v62, v62, v53
	v_add_f32_e32 v63, v63, v59
	v_lshlrev_b32_e32 v34, 16, v98
	v_and_b32_e32 v52, 0xffff0000, v98
	v_lshlrev_b32_e32 v53, 16, v99
	v_and_b32_e32 v59, 0xffff0000, v99
	v_add_f32_e32 v60, v60, v34
	v_add_f32_e32 v61, v61, v52
	v_add_f32_e32 v62, v62, v53
	v_add_f32_e32 v63, v63, v59
	v_lshlrev_b32_e32 v34, 16, v106
	v_and_b32_e32 v52, 0xffff0000, v106
	v_lshlrev_b32_e32 v53, 16, v107
	v_and_b32_e32 v59, 0xffff0000, v107
	v_add_f32_e32 v60, v60, v34
	v_add_f32_e32 v61, v61, v52
	v_add_f32_e32 v62, v62, v53
	v_add_f32_e32 v63, v63, v59
	v_lshlrev_b32_e32 v34, 16, v114
	v_and_b32_e32 v52, 0xffff0000, v114
	v_lshlrev_b32_e32 v53, 16, v115
	v_and_b32_e32 v59, 0xffff0000, v115
	v_add_f32_e32 v60, v60, v34
	v_add_f32_e32 v61, v61, v52
	v_add_f32_e32 v62, v62, v53
	v_add_f32_e32 v63, v63, v59
	v_lshlrev_b32_e32 v34, 16, v122
	v_and_b32_e32 v52, 0xffff0000, v122
	v_lshlrev_b32_e32 v53, 16, v123
	v_and_b32_e32 v59, 0xffff0000, v123
	v_add_f32_e32 v60, v60, v34
	v_add_f32_e32 v61, v61, v52
	v_add_f32_e32 v62, v62, v53
	v_add_f32_e32 v63, v63, v59
	v_lshlrev_b32_e32 v34, 16, v28
	v_and_b32_e32 v52, 0xffff0000, v28
	v_lshlrev_b32_e32 v53, 16, v29
	v_and_b32_e32 v59, 0xffff0000, v29
	v_fma_f32 v40, v60, v22, v34
	v_fma_f32 v41, v61, v22, v52
	v_fma_f32 v42, v62, v22, v53
	v_fma_f32 v43, v63, v22, v59
	v_mul_f32_e32 v34, v40, v40
	v_fma_f32 v34, v41, v41, v34
	v_mul_f32_e32 v52, v42, v42
	v_fma_f32 v52, v43, v43, v52
	v_add_f32_e32 v34, v34, v52
	v_add_f32_e32 v23, v23, v34
	v_mov_b32_e32 v60, 0
	v_mov_b32_e32 v61, 0
	v_mov_b32_e32 v62, 0
	v_mov_b32_e32 v63, 0
	v_lshlrev_b32_e32 v34, 16, v68
	v_and_b32_e32 v52, 0xffff0000, v68
	v_lshlrev_b32_e32 v53, 16, v69
	v_and_b32_e32 v59, 0xffff0000, v69
	v_add_f32_e32 v60, v60, v34
	v_add_f32_e32 v61, v61, v52
	v_add_f32_e32 v62, v62, v53
	v_add_f32_e32 v63, v63, v59
	v_lshlrev_b32_e32 v34, 16, v76
	v_and_b32_e32 v52, 0xffff0000, v76
	v_lshlrev_b32_e32 v53, 16, v77
	v_and_b32_e32 v59, 0xffff0000, v77
	v_add_f32_e32 v60, v60, v34
	v_add_f32_e32 v61, v61, v52
	v_add_f32_e32 v62, v62, v53
	v_add_f32_e32 v63, v63, v59
	v_lshlrev_b32_e32 v34, 16, v84
	v_and_b32_e32 v52, 0xffff0000, v84
	v_lshlrev_b32_e32 v53, 16, v85
	v_and_b32_e32 v59, 0xffff0000, v85
	v_add_f32_e32 v60, v60, v34
	v_add_f32_e32 v61, v61, v52
	v_add_f32_e32 v62, v62, v53
	v_add_f32_e32 v63, v63, v59
	v_lshlrev_b32_e32 v34, 16, v92
	v_and_b32_e32 v52, 0xffff0000, v92
	v_lshlrev_b32_e32 v53, 16, v93
	v_and_b32_e32 v59, 0xffff0000, v93
	v_add_f32_e32 v60, v60, v34
	v_add_f32_e32 v61, v61, v52
	v_add_f32_e32 v62, v62, v53
	v_add_f32_e32 v63, v63, v59
	v_lshlrev_b32_e32 v34, 16, v100
	v_and_b32_e32 v52, 0xffff0000, v100
	v_lshlrev_b32_e32 v53, 16, v101
	v_and_b32_e32 v59, 0xffff0000, v101
	v_add_f32_e32 v60, v60, v34
	v_add_f32_e32 v61, v61, v52
	v_add_f32_e32 v62, v62, v53
	v_add_f32_e32 v63, v63, v59
	v_lshlrev_b32_e32 v34, 16, v108
	v_and_b32_e32 v52, 0xffff0000, v108
	v_lshlrev_b32_e32 v53, 16, v109
	v_and_b32_e32 v59, 0xffff0000, v109
	v_add_f32_e32 v60, v60, v34
	v_add_f32_e32 v61, v61, v52
	v_add_f32_e32 v62, v62, v53
	v_add_f32_e32 v63, v63, v59
	v_lshlrev_b32_e32 v34, 16, v116
	v_and_b32_e32 v52, 0xffff0000, v116
; __device__ __forceinline__ float bf_lo(unsigned w) { return __uint_as_float(w << 16); }
; __device__ __forceinline__ float bf_hi(unsigned w) { return __uint_as_float(w & 0xffff0000u); }
; __device__ __forceinline__ unsigned pk2(float lo, float hi) { return pg8::cvt_pk_bf16(lo, hi); }
; __device__ __forceinline__ void phase_sample_finalize(const Args& a, unsigned char* ws, int G, const int bid, const int tid) {
;     ...
;         for (int j = 0; j < 4; ++j) { const u32x2 w = ((const u32x2*)(XB + (size_t)m * DM))[lane + 64 * j]; f32x4 v = {pg8::bf_lo(w.x), pg8::bf_hi(w.x), pg8::bf_lo(w.y), pg8::bf_hi(w.y)};
;             f32x4 p = {0.f, 0.f, 0.f, 0.f};
; #pragma unroll
;             for (int z = 0; z < 8; ++z) { const u32x2 sw = ((const u32x2*)(SL + ((size_t)z * MS + r) * DM))[lane + 64 * j]; p += (f32x4){pg8::bf_lo(sw.x), pg8::bf_hi(sw.x), pg8::bf_lo(sw.y), pg8::bf_hi(sw.y)}; }
;             v += p * r2;
;             ss += (v.x * v.x + v.y * v.y) + (v.z * v.z + v.w * v.w); o[j] = (u32x2){pk2(v.x, v.y), pk2(v.z, v.w)}; }
; #pragma unroll
;         for (int j = 0; j < 4; ++j) ((u32x2*)(XB + (size_t)m * DM))[lane + 64 * j] = o[j];
;         ss = wave_sum(ss);
;         if (lane == 0) rsq[m] = ss;
	v_lshlrev_b32_e32 v53, 16, v117
	v_and_b32_e32 v59, 0xffff0000, v117
	v_add_f32_e32 v60, v60, v34
	v_add_f32_e32 v61, v61, v52
	v_add_f32_e32 v62, v62, v53
	v_add_f32_e32 v63, v63, v59
	v_lshlrev_b32_e32 v34, 16, v124
	v_and_b32_e32 v52, 0xffff0000, v124
	v_lshlrev_b32_e32 v53, 16, v125
	v_and_b32_e32 v59, 0xffff0000, v125
	v_add_f32_e32 v60, v60, v34
	v_add_f32_e32 v61, v61, v52
	v_add_f32_e32 v62, v62, v53
	v_add_f32_e32 v63, v63, v59
	v_lshlrev_b32_e32 v34, 16, v30
	v_and_b32_e32 v52, 0xffff0000, v30
	v_lshlrev_b32_e32 v53, 16, v31
	v_and_b32_e32 v59, 0xffff0000, v31
	v_fma_f32 v44, v60, v22, v34
	v_fma_f32 v45, v61, v22, v52
	v_fma_f32 v46, v62, v22, v53
	v_fma_f32 v47, v63, v22, v59
	v_mul_f32_e32 v34, v44, v44
	v_fma_f32 v34, v45, v45, v34
	v_mul_f32_e32 v52, v46, v46
	v_fma_f32 v52, v47, v47, v52
	v_add_f32_e32 v34, v34, v52
	v_add_f32_e32 v23, v23, v34
	v_mov_b32_e32 v60, 0
	v_mov_b32_e32 v61, 0
	v_mov_b32_e32 v62, 0
	v_mov_b32_e32 v63, 0
	v_lshlrev_b32_e32 v34, 16, v70
	v_and_b32_e32 v52, 0xffff0000, v70
	v_lshlrev_b32_e32 v53, 16, v71
	v_and_b32_e32 v59, 0xffff0000, v71
	v_add_f32_e32 v60, v60, v34
	v_add_f32_e32 v61, v61, v52
	v_add_f32_e32 v62, v62, v53
	v_add_f32_e32 v63, v63, v59
	v_lshlrev_b32_e32 v34, 16, v78
	v_and_b32_e32 v52, 0xffff0000, v78
	v_lshlrev_b32_e32 v53, 16, v79
	v_and_b32_e32 v59, 0xffff0000, v79
	v_add_f32_e32 v60, v60, v34
	v_add_f32_e32 v61, v61, v52
	v_add_f32_e32 v62, v62, v53
	v_add_f32_e32 v63, v63, v59
	v_lshlrev_b32_e32 v34, 16, v86
	v_and_b32_e32 v52, 0xffff0000, v86
	v_lshlrev_b32_e32 v53, 16, v87
	v_and_b32_e32 v59, 0xffff0000, v87
	v_add_f32_e32 v60, v60, v34
	v_add_f32_e32 v61, v61, v52
	v_add_f32_e32 v62, v62, v53
	v_add_f32_e32 v63, v63, v59
	v_lshlrev_b32_e32 v34, 16, v94
	v_and_b32_e32 v52, 0xffff0000, v94
	v_lshlrev_b32_e32 v53, 16, v95
	v_and_b32_e32 v59, 0xffff0000, v95
	v_add_f32_e32 v60, v60, v34
	v_add_f32_e32 v61, v61, v52
	v_add_f32_e32 v62, v62, v53
	v_add_f32_e32 v63, v63, v59
	v_lshlrev_b32_e32 v34, 16, v102
	v_and_b32_e32 v52, 0xffff0000, v102
	v_lshlrev_b32_e32 v53, 16, v103
	v_and_b32_e32 v59, 0xffff0000, v103
	v_add_f32_e32 v60, v60, v34
	v_add_f32_e32 v61, v61, v52
	v_add_f32_e32 v62, v62, v53
	v_add_f32_e32 v63, v63, v59
	v_lshlrev_b32_e32 v34, 16, v110
	v_and_b32_e32 v52, 0xffff0000, v110
	v_lshlrev_b32_e32 v53, 16, v111
	v_and_b32_e32 v59, 0xffff0000, v111
	v_add_f32_e32 v60, v60, v34
	v_add_f32_e32 v61, v61, v52
	v_add_f32_e32 v62, v62, v53
	v_add_f32_e32 v63, v63, v59
	v_lshlrev_b32_e32 v34, 16, v118
	v_and_b32_e32 v52, 0xffff0000, v118
	v_lshlrev_b32_e32 v53, 16, v119
	v_and_b32_e32 v59, 0xffff0000, v119
	v_add_f32_e32 v60, v60, v34
	v_add_f32_e32 v61, v61, v52
	v_add_f32_e32 v62, v62, v53
	v_add_f32_e32 v63, v63, v59
	v_lshlrev_b32_e32 v34, 16, v126
	v_and_b32_e32 v52, 0xffff0000, v126
	v_lshlrev_b32_e32 v53, 16, v127
	v_and_b32_e32 v59, 0xffff0000, v127
	v_add_f32_e32 v60, v60, v34
	v_add_f32_e32 v61, v61, v52
	v_add_f32_e32 v62, v62, v53
	v_add_f32_e32 v63, v63, v59
	v_lshlrev_b32_e32 v34, 16, v32
	v_and_b32_e32 v52, 0xffff0000, v32
	v_lshlrev_b32_e32 v53, 16, v33
	v_and_b32_e32 v59, 0xffff0000, v33
	v_fma_f32 v48, v60, v22, v34
	v_fma_f32 v49, v61, v22, v52
	v_fma_f32 v50, v62, v22, v53
	v_fma_f32 v51, v63, v22, v59
	v_mul_f32_e32 v34, v48, v48
	v_fma_f32 v34, v49, v49, v34
	v_mul_f32_e32 v52, v50, v50
	v_fma_f32 v52, v51, v51, v52
	v_add_f32_e32 v34, v34, v52
	v_add_f32_e32 v23, v23, v34
	v_cvt_pk_bf16_f32 v64, v36, v37
	v_cvt_pk_bf16_f32 v65, v38, v39
	v_cvt_pk_bf16_f32 v66, v40, v41
	v_cvt_pk_bf16_f32 v67, v42, v43
	v_cvt_pk_bf16_f32 v68, v44, v45
	v_cvt_pk_bf16_f32 v69, v46, v47
	v_cvt_pk_bf16_f32 v70, v48, v49
	v_cvt_pk_bf16_f32 v71, v50, v51
	global_store_dwordx2 v16, v[64:65], s[12:13] offset:0
	global_store_dwordx2 v16, v[66:67], s[12:13] offset:512
	global_store_dwordx2 v16, v[68:69], s[12:13] offset:1024
	global_store_dwordx2 v16, v[70:71], s[12:13] offset:1536
	v_xor_b32_e32 v52, 4, v17
	ds_bpermute_b32 v34, v52, v23
	s_waitcnt lgkmcnt(0)
	v_add_f32_e32 v23, v23, v34
	v_xor_b32_e32 v52, 8, v17
	ds_bpermute_b32 v34, v52, v23
	s_waitcnt lgkmcnt(0)
	v_add_f32_e32 v23, v23, v34
	v_xor_b32_e32 v52, 16, v17
	ds_bpermute_b32 v34, v52, v23
	s_waitcnt lgkmcnt(0)
	v_add_f32_e32 v23, v23, v34
	v_xor_b32_e32 v52, 32, v17
	ds_bpermute_b32 v34, v52, v23
	s_waitcnt lgkmcnt(0)
	v_add_f32_e32 v23, v23, v34
	v_xor_b32_e32 v52, 64, v17
	ds_bpermute_b32 v34, v52, v23
	s_waitcnt lgkmcnt(0)
	v_add_f32_e32 v23, v23, v34
	v_xor_b32_e32 v52, 128, v17
	ds_bpermute_b32 v34, v52, v23
	s_waitcnt lgkmcnt(0)
	v_add_f32_e32 v23, v23, v34
	s_add_u32 s14, s14, 0x84000
	s_addc_u32 s15, s15, 0
	v_mov_b32_e32 v34, 0
	global_store_dword v34, v23, s[14:15]
	s_branch .Lmid_next
